# phase 6 row loop unrolled x2 with rows fetched two rows ahead into two spare register sets
# baseline (speedup 1.0000x reference)
; DI float bflo(unsigned u) { return __uint_as_float(u << 16); }
; DI float bfhi(unsigned u) { return __uint_as_float(u & 0xffff0000u); }
; DI void phase6(const Params& p) {
;     const int lane = VTID & 63, w = VTID >> 6;
;     const float* x = p.in[0]; const float* gpost = p.in[15]; const float* gffn = p.in[16];
;     const bf16_t* MIX = (const bf16_t*)(p.ws + OFF_MIX);
;     bf16_t* H = (bf16_t*)(p.ws + OFF_H);
;     float* RSTD = (float*)(p.ws + OFF_GATES);
;     for (int row = VBLK * 4 + w; row < T; row += VGRID * 4) {
;         f32x4 mv[4], xv[4]; float ss = 0.f;
; #pragma unroll
;         for (int i = 0; i < 4; ++i) {
;             const u32x2 u = *(const u32x2*)(MIX + (size_t)row * 1024 + i * 256 + lane * 4);
;             mv[i][0] = bflo(u.x); mv[i][1] = bfhi(u.x); mv[i][2] = bflo(u.y); mv[i][3] = bfhi(u.y);
;             xv[i] = *(const f32x4*)(x + (size_t)row * 1024 + i * 256 + lane * 4);
.LBB0_702:
	s_cmp_gt_i32 s90, 6
	s_cselect_b64 s[0:1], -1, 0
	s_cmp_lt_i32 s91, 7
	s_cselect_b64 s[2:3], -1, 0
	s_or_b64 s[0:1], s[0:1], s[2:3]
	v_bfe_u32 v1, v0, 6, 4
	s_and_b64 vcc, exec, s[0:1]
	v_and_b32_e32 v150, 4, v1
	s_cbranch_vccnz .LBB0_758
	v_and_b32_e32 v56, 0x3ff, v0
	v_readlane_b32 s0, v238, 0
	v_bfe_u32 v1, v56, 6, 2
	s_lshl_b32 s0, s0, 3
	v_or3_b32 v18, v150, s0, v1
	s_mov_b32 s0, 0x8000
	v_cmp_gt_i32_e32 vcc, s0, v18
	s_and_saveexec_b64 s[2:3], vcc
	s_cbranch_execz .LBB0_708
	v_mbcnt_lo_u32_b32 v2, -1, 0
	v_mbcnt_hi_u32_b32 v2, -1, v2
	v_and_b32_e32 v4, 64, v2
	v_xor_b32_e32 v3, 32, v2
	v_add_u32_e32 v4, 64, v4
	v_cmp_lt_i32_e32 vcc, v3, v4
	v_readlane_b32 s4, v238, 31
	v_readlane_b32 s5, v238, 32
	v_cndmask_b32_e32 v3, v2, v3, vcc
	v_lshlrev_b32_e32 v57, 2, v3
	v_xor_b32_e32 v3, 16, v2
	v_cmp_lt_i32_e32 vcc, v3, v4
	v_readlane_b32 s6, v238, 33
	v_readlane_b32 s7, v238, 34
	v_cndmask_b32_e32 v3, v2, v3, vcc
	v_lshlrev_b32_e32 v58, 2, v3
	v_xor_b32_e32 v3, 8, v2
	v_cmp_lt_i32_e32 vcc, v3, v4
	v_readlane_b32 s8, v238, 35
	v_readlane_b32 s9, v238, 36
	v_cndmask_b32_e32 v3, v2, v3, vcc
	v_lshlrev_b32_e32 v59, 2, v3
	v_xor_b32_e32 v3, 4, v2
	v_cmp_lt_i32_e32 vcc, v3, v4
	v_readlane_b32 s10, v238, 37
	v_readlane_b32 s11, v238, 38
	v_cndmask_b32_e32 v3, v2, v3, vcc
	v_lshlrev_b32_e32 v60, 2, v3
	v_xor_b32_e32 v3, 2, v2
	v_cmp_lt_i32_e32 vcc, v3, v4
	v_and_b32_e32 v1, 63, v56
	v_readlane_b32 s4, v238, 1
	v_cndmask_b32_e32 v3, v2, v3, vcc
	v_lshlrev_b32_e32 v61, 2, v3
	v_xor_b32_e32 v3, 1, v2
	v_cmp_lt_i32_e32 vcc, v3, v4
	v_readlane_b32 s12, v238, 39
	v_readlane_b32 s13, v238, 40
	v_cndmask_b32_e32 v2, v2, v3, vcc
	v_lshlrev_b32_e32 v62, 2, v2
	v_lshlrev_b32_e32 v2, 4, v1
	v_mov_b32_e32 v3, 0
	v_readlane_b32 s14, v238, 41
	v_readlane_b32 s15, v238, 42
	v_readlane_b32 s16, v238, 43
	v_readlane_b32 s17, v238, 44
	v_readlane_b32 s18, v238, 45
	v_readlane_b32 s19, v238, 46
	v_readlane_b32 s5, v238, 2
	v_ashrrev_i32_e32 v19, 31, v18
	v_mov_b64_e32 v[4:5], 0x18ba5800
	v_lshl_add_u64 v[20:21], s[18:19], 0, v[2:3]
	v_readlane_b32 s6, v238, 3
	v_lshl_add_u64 v[22:23], s[4:5], 0, v[2:3]
	v_readlane_b32 s4, v238, 10
	v_lshl_add_u64 v[24:25], v[18:19], 2, v[4:5]
	v_lshlrev_b64 v[4:5], 12, v[18:19]
	v_readlane_b32 s12, v238, 15
	v_readlane_b32 s7, v238, 4
	v_readlane_b32 s5, v238, 11
	s_lshl_b32 s6, s4, 3
	v_or_b32_e32 v4, v4, v2
	v_readlane_b32 s13, v238, 16
	v_readlane_b32 s8, v238, 5
	v_readlane_b32 s9, v238, 6
	v_readlane_b32 s10, v238, 7
	v_readlane_b32 s11, v238, 8
	s_ashr_i32 s7, s6, 31
	v_lshlrev_b64 v[26:27], 11, v[18:19]
	v_readlane_b32 s14, v238, 17
	v_readlane_b32 s15, v238, 18
	v_readlane_b32 s16, v238, 19
	v_readlane_b32 s17, v238, 20
	v_lshl_add_u64 v[2:3], s[12:13], 0, v[4:5]
	s_mov_b64 s[4:5], 0xc00
	v_cmp_eq_u32_e64 s[0:1], 0, v1
	s_lshl_b64 s[8:9], s[6:7], 2
	v_lshl_or_b32 v26, v1, 3, v26
	s_lshl_b64 s[10:11], s[6:7], 11
	v_lshl_add_u64 v[28:29], v[2:3], 0, s[4:5]
	s_lshl_b64 s[12:13], s[6:7], 12
	s_mov_b64 s[14:15], 0
	v_mov_b32_e32 v63, 0x358637bd
	s_mov_b32 s7, 0x800000
	s_mov_b32 s16, 0x1ba5000
	s_movk_i32 s17, 0x7fff
	v_readlane_b32 s18, v238, 21
	v_readlane_b32 s19, v238, 22
	v_readlane_b32 s20, v238, 23
	v_readlane_b32 s21, v238, 24
	v_readlane_b32 s22, v238, 25
	v_readlane_b32 s23, v238, 26
	v_readlane_b32 s24, v238, 27
	v_readlane_b32 s25, v238, 28
	v_readlane_b32 s26, v238, 29
	v_readlane_b32 s27, v238, 30
	global_load_dwordx4 v[200:203], v[20:21], off
	global_load_dwordx4 v[204:207], v[20:21], off offset:1024
	global_load_dwordx4 v[208:211], v[20:21], off offset:2048
	global_load_dwordx4 v[212:215], v[20:21], off offset:3072
	global_load_dwordx4 v[216:219], v[22:23], off
	global_load_dwordx4 v[220:223], v[22:23], off offset:1024
	global_load_dwordx4 v[224:227], v[22:23], off offset:2048
	global_load_dwordx4 v[228:231], v[22:23], off offset:3072
	v_lshl_add_u64 v[124:125], s[88:89], 0, v[26:27]
	v_add_co_u32_e32 v124, vcc, 0x9ba5000, v124
	s_nop 1
	v_addc_co_u32_e32 v125, vcc, 0, v125, vcc
	v_mov_b32_e32 v126, v28
	v_mov_b32_e32 v127, v29
	global_load_dwordx2 v[70:71], v[124:125], off offset:2048
	global_load_dwordx2 v[72:73], v[124:125], off offset:2560
	global_load_dwordx2 v[74:75], v[124:125], off offset:3072
	global_load_dwordx2 v[76:77], v[124:125], off offset:3584
	global_load_dwordx4 v[80:83], v[126:127], off offset:-3072
	global_load_dwordx4 v[84:87], v[126:127], off offset:-2048
	global_load_dwordx4 v[88:91], v[126:127], off offset:-1024
	global_load_dwordx4 v[92:95], v[126:127], off
	v_lshl_add_u64 v[124:125], v[124:125], 0, s[10:11]
	v_lshl_add_u64 v[126:127], v[126:127], 0, s[12:13]
	global_load_dwordx2 v[100:101], v[124:125], off offset:2048
	global_load_dwordx2 v[102:103], v[124:125], off offset:2560
	global_load_dwordx2 v[104:105], v[124:125], off offset:3072
	global_load_dwordx2 v[106:107], v[124:125], off offset:3584
	global_load_dwordx4 v[108:111], v[126:127], off offset:-3072
	global_load_dwordx4 v[112:115], v[126:127], off offset:-2048
	global_load_dwordx4 v[116:119], v[126:127], off offset:-1024
	global_load_dwordx4 v[120:123], v[126:127], off
	s_waitcnt vmcnt(8)
.Lp6_topA:
	v_lshl_add_u64 v[30:31], s[88:89], 0, v[26:27]
	v_mov_b32_e32 v34, v70
	v_mov_b32_e32 v35, v71
	v_mov_b32_e32 v38, v72
	v_mov_b32_e32 v39, v73
	v_mov_b32_e32 v42, v74
	v_mov_b32_e32 v43, v75
	v_mov_b32_e32 v54, v76
	v_mov_b32_e32 v55, v77
	v_mov_b32_e32 v14, v80
	v_mov_b32_e32 v15, v81
	v_mov_b32_e32 v16, v82
	v_mov_b32_e32 v17, v83
	v_mov_b32_e32 v10, v84
	v_mov_b32_e32 v11, v85
	v_mov_b32_e32 v12, v86
	v_mov_b32_e32 v13, v87
	v_mov_b32_e32 v2, v88
	v_mov_b32_e32 v3, v89
	v_mov_b32_e32 v4, v90
	v_mov_b32_e32 v5, v91
	v_mov_b32_e32 v6, v92
	v_mov_b32_e32 v7, v93
	v_mov_b32_e32 v8, v94
	v_mov_b32_e32 v9, v95
	v_add_u32_e32 v124, s6, v18
	v_add_u32_e32 v124, s6, v124
	v_cmp_ge_i32_e32 vcc, s17, v124
	s_and_saveexec_b64 s[98:99], vcc
	s_cbranch_execz .Lp6_nopfA
	v_lshl_add_u64 v[124:125], v[30:31], 0, s[10:11]
	v_lshl_add_u64 v[124:125], v[124:125], 0, s[10:11]
	v_add_co_u32_e32 v124, vcc, 0x9ba5000, v124
	s_nop 1
	v_addc_co_u32_e32 v125, vcc, 0, v125, vcc
	v_lshl_add_u64 v[126:127], v[28:29], 0, s[12:13]
	v_lshl_add_u64 v[126:127], v[126:127], 0, s[12:13]
	global_load_dwordx2 v[70:71], v[124:125], off offset:2048
	global_load_dwordx2 v[72:73], v[124:125], off offset:2560
	global_load_dwordx2 v[74:75], v[124:125], off offset:3072
	global_load_dwordx2 v[76:77], v[124:125], off offset:3584
	global_load_dwordx4 v[80:83], v[126:127], off offset:-3072
	global_load_dwordx4 v[84:87], v[126:127], off offset:-2048
	global_load_dwordx4 v[88:91], v[126:127], off offset:-1024
	global_load_dwordx4 v[92:95], v[126:127], off
	s_branch .Lp6_pfdA

; DI float bflo(unsigned u) { return __uint_as_float(u << 16); }
; DI float bfhi(unsigned u) { return __uint_as_float(u & 0xffff0000u); }
; DI float wave_sum(float v) {
;     v += __shfl_xor(v, 32); v += __shfl_xor(v, 16); v += __shfl_xor(v, 8);
;     v += __shfl_xor(v, 4); v += __shfl_xor(v, 2); v += __shfl_xor(v, 1);
;     return v;
; }
; DI void phase6(const Params& p) {
;     ...
;             const u32x2 u = *(const u32x2*)(MIX + (size_t)row * 1024 + i * 256 + lane * 4);
;             mv[i][0] = bflo(u.x); mv[i][1] = bfhi(u.x); mv[i][2] = bflo(u.y); mv[i][3] = bfhi(u.y);
;             xv[i] = *(const f32x4*)(x + (size_t)row * 1024 + i * 256 + lane * 4);
;             ss += mv[i][0] * mv[i][0] + mv[i][1] * mv[i][1] + mv[i][2] * mv[i][2] + mv[i][3] * mv[i][3];
;         }
;         ss = wave_sum(ss);
;         const float rstd = rsqrtf(ss * (1.f / 1024.f) + NORM_EPS);
;         if (lane == 0) RSTD[row] = rstd;
.Lp6_pfdA:
	s_or_b64 exec, exec, s[98:99]
	v_and_b32_e32 v1, 0xffff0000, v34
	v_lshlrev_b32_e32 v36, 16, v38
	v_and_b32_e32 v49, 0xffff0000, v38
	v_and_b32_e32 v45, 0xffff0000, v42
	v_mov_b32_e32 v48, v1
	v_lshlrev_b32_e32 v32, 16, v34
	v_lshlrev_b32_e32 v38, 16, v39
	v_lshlrev_b32_e32 v44, 16, v54
	v_and_b32_e32 v53, 0xffff0000, v54
	v_mov_b32_e32 v33, v36
	v_mov_b32_e32 v52, v45
	v_pk_mul_f32 v[64:65], v[48:49], v[48:49]
	v_lshlrev_b32_e32 v34, 16, v35
	v_and_b32_e32 v19, 0xffff0000, v35
	v_lshlrev_b32_e32 v40, 16, v42
	v_lshlrev_b32_e32 v46, 16, v55
	v_mov_b32_e32 v35, v38
	v_mov_b32_e32 v41, v44
	v_pk_mul_f32 v[66:67], v[52:53], v[52:53]
	v_pk_fma_f32 v[64:65], v[32:33], v[32:33], v[64:65]
	v_and_b32_e32 v51, 0xffff0000, v39
	v_lshlrev_b32_e32 v42, 16, v43
	v_and_b32_e32 v47, 0xffff0000, v43
	v_mov_b32_e32 v50, v19
	v_mov_b32_e32 v43, v46
	v_pk_fma_f32 v[66:67], v[40:41], v[40:41], v[66:67]
	v_pk_fma_f32 v[64:65], v[34:35], v[34:35], v[64:65]
	v_and_b32_e32 v55, 0xffff0000, v55
	v_mov_b32_e32 v54, v47
	v_pk_fma_f32 v[66:67], v[42:43], v[42:43], v[66:67]
	v_pk_fma_f32 v[64:65], v[50:51], v[50:51], v[64:65]
	v_pk_fma_f32 v[66:67], v[54:55], v[54:55], v[66:67]
	v_add_f32_e32 v33, v64, v65
	v_add_f32_e32 v33, v33, v66
	v_add_f32_e32 v33, v33, v67
	ds_bpermute_b32 v35, v57, v33
	s_waitcnt lgkmcnt(0)
	v_add_f32_e32 v33, v33, v35
	ds_bpermute_b32 v35, v58, v33
	s_waitcnt lgkmcnt(0)
	v_add_f32_e32 v33, v33, v35
	ds_bpermute_b32 v35, v59, v33
	s_waitcnt lgkmcnt(0)
	v_add_f32_e32 v33, v33, v35
	ds_bpermute_b32 v35, v60, v33
	s_waitcnt lgkmcnt(0)
	v_add_f32_e32 v33, v33, v35
	ds_bpermute_b32 v35, v61, v33
	s_waitcnt lgkmcnt(0)
	v_add_f32_e32 v33, v33, v35
	ds_bpermute_b32 v35, v62, v33
	s_waitcnt lgkmcnt(0)
	v_add_f32_e32 v33, v33, v35
	v_fmamk_f32 v33, v33, 0x3a800000, v63
	v_mul_f32_e32 v35, 0x4b800000, v33
	v_cmp_gt_f32_e32 vcc, s7, v33
	s_nop 1
	v_cndmask_b32_e32 v33, v33, v35, vcc
	v_rsq_f32_e32 v33, v33
	s_nop 0
	v_mul_f32_e32 v35, 0x45800000, v33
	v_cndmask_b32_e32 v48, v33, v35, vcc
	s_waitcnt vmcnt(8)
	s_and_saveexec_b64 s[4:5], s[0:1]
	s_cbranch_execz .Lp6_705A
	v_lshl_add_u64 v[64:65], s[88:89], 0, v[24:25]
	global_store_dword v[64:65], v48, off
	s_branch .Lp6_705A

; DI float bflo(unsigned u) { return __uint_as_float(u << 16); }
; DI float bfhi(unsigned u) { return __uint_as_float(u & 0xffff0000u); }
; DI void phase6(const Params& p) {
;     ...
;     for (int row = VBLK * 4 + w; row < T; row += VGRID * 4) {
;         f32x4 mv[4], xv[4]; float ss = 0.f;
; #pragma unroll
;         for (int i = 0; i < 4; ++i) {
;             const u32x2 u = *(const u32x2*)(MIX + (size_t)row * 1024 + i * 256 + lane * 4);
;             mv[i][0] = bflo(u.x); mv[i][1] = bfhi(u.x); mv[i][2] = bflo(u.y); mv[i][3] = bfhi(u.y);
;             xv[i] = *(const f32x4*)(x + (size_t)row * 1024 + i * 256 + lane * 4);
.Lp6_topB:
	v_lshl_add_u64 v[30:31], s[88:89], 0, v[26:27]
	v_mov_b32_e32 v34, v100
	v_mov_b32_e32 v35, v101
	v_mov_b32_e32 v38, v102
	v_mov_b32_e32 v39, v103
	v_mov_b32_e32 v42, v104
	v_mov_b32_e32 v43, v105
	v_mov_b32_e32 v54, v106
	v_mov_b32_e32 v55, v107
	v_mov_b32_e32 v14, v108
	v_mov_b32_e32 v15, v109
	v_mov_b32_e32 v16, v110
	v_mov_b32_e32 v17, v111
	v_mov_b32_e32 v10, v112
	v_mov_b32_e32 v11, v113
	v_mov_b32_e32 v12, v114
	v_mov_b32_e32 v13, v115
	v_mov_b32_e32 v2, v116
	v_mov_b32_e32 v3, v117
	v_mov_b32_e32 v4, v118
	v_mov_b32_e32 v5, v119
	v_mov_b32_e32 v6, v120
	v_mov_b32_e32 v7, v121
	v_mov_b32_e32 v8, v122
	v_mov_b32_e32 v9, v123
	v_add_u32_e32 v124, s6, v18
	v_add_u32_e32 v124, s6, v124
	v_cmp_ge_i32_e32 vcc, s17, v124
	s_and_saveexec_b64 s[98:99], vcc
	s_cbranch_execz .Lp6_nopfB
	v_lshl_add_u64 v[124:125], v[30:31], 0, s[10:11]
	v_lshl_add_u64 v[124:125], v[124:125], 0, s[10:11]
	v_add_co_u32_e32 v124, vcc, 0x9ba5000, v124
	s_nop 1
	v_addc_co_u32_e32 v125, vcc, 0, v125, vcc
	v_lshl_add_u64 v[126:127], v[28:29], 0, s[12:13]
	v_lshl_add_u64 v[126:127], v[126:127], 0, s[12:13]
	global_load_dwordx2 v[100:101], v[124:125], off offset:2048
	global_load_dwordx2 v[102:103], v[124:125], off offset:2560
	global_load_dwordx2 v[104:105], v[124:125], off offset:3072
	global_load_dwordx2 v[106:107], v[124:125], off offset:3584
	global_load_dwordx4 v[108:111], v[126:127], off offset:-3072
	global_load_dwordx4 v[112:115], v[126:127], off offset:-2048
	global_load_dwordx4 v[116:119], v[126:127], off offset:-1024
	global_load_dwordx4 v[120:123], v[126:127], off
	s_branch .Lp6_pfdB

; DI unsigned pk_bf16(float a, float b) { f32x2 v = {a, b}; return __builtin_bit_cast(unsigned, __builtin_convertvector(v, bf16v2)); }
; DI void phase6(const Params& p) {
;     ...
;         float ss2 = 0.f;
; #pragma unroll
;         for (int i = 0; i < 4; ++i) {
;             const f32x4 gg = *(const f32x4*)(gpost + i * 256 + lane * 4);
; #pragma unroll
;             for (int e = 0; e < 4; ++e) { xv[i][e] += mv[i][e] * rstd * gg[e]; ss2 += xv[i][e] * xv[i][e]; }
;         }
;         ss2 = wave_sum(ss2);
;         const float rstd2 = rsqrtf(ss2 * (1.f / 1024.f) + NORM_EPS);
; #pragma unroll
;         for (int i = 0; i < 4; ++i) {
;             const f32x4 gg = *(const f32x4*)(gffn + i * 256 + lane * 4);
;             u32x2 o; o.x = pk_bf16(xv[i][0] * rstd2 * gg[0], xv[i][1] * rstd2 * gg[1]); o.y = pk_bf16(xv[i][2] * rstd2 * gg[2], xv[i][3] * rstd2 * gg[3]);
;             *(u32x2*)(H + (size_t)row * 1024 + i * 256 + lane * 4) = o;
;         }
.Lp6_705B:
	s_or_b64 exec, exec, s[4:5]
	v_mov_b32_e32 v39, v51
	v_mov_b32_e32 v41, v45
	v_mov_b32_e32 v45, v53
	v_mov_b32_e32 v33, v1
	v_mov_b32_e32 v35, v19
	v_mov_b32_e32 v43, v47
	v_pk_mul_f32 v[32:33], v[48:49], v[32:33] op_sel_hi:[0,1]
	v_pk_mul_f32 v[34:35], v[48:49], v[34:35] op_sel_hi:[0,1]
	v_pk_mul_f32 v[42:43], v[48:49], v[42:43] op_sel_hi:[0,1]
	v_mov_b32_e32 v37, v49
	v_pk_mul_f32 v[40:41], v[48:49], v[40:41] op_sel_hi:[0,1]
	v_pk_mul_f32 v[36:37], v[48:49], v[36:37] op_sel_hi:[0,1]
	v_pk_mul_f32 v[38:39], v[48:49], v[38:39] op_sel_hi:[0,1]
	v_mov_b32_e32 v47, v55
	v_pk_mul_f32 v[44:45], v[48:49], v[44:45] op_sel_hi:[0,1]
	v_pk_mul_f32 v[46:47], v[48:49], v[46:47] op_sel_hi:[0,1]
	v_add_co_u32_e64 v30, s[4:5], s16, v30
	v_add_u32_e32 v18, s6, v18
	s_nop 0
	v_addc_co_u32_e64 v31, s[4:5], 0, v31, s[4:5]
	v_lshl_add_u64 v[24:25], v[24:25], 0, s[8:9]
	v_lshl_add_u64 v[26:27], v[26:27], 0, s[10:11]
	v_lshl_add_u64 v[28:29], v[28:29], 0, s[12:13]
	v_pk_fma_f32 v[14:15], v[32:33], v[200:201], v[14:15]
	v_pk_fma_f32 v[16:17], v[34:35], v[202:203], v[16:17]
	v_pk_fma_f32 v[32:33], v[42:43], v[210:211], v[4:5]
	v_pk_mul_f32 v[4:5], v[14:15], v[14:15]
	v_pk_fma_f32 v[34:35], v[40:41], v[208:209], v[2:3]
	v_pk_mul_f32 v[2:3], v[16:17], v[16:17]
	v_add_f32_e32 v1, v4, v5
	v_pk_fma_f32 v[10:11], v[36:37], v[204:205], v[10:11]
	v_add_f32_e32 v1, v2, v1
	v_pk_fma_f32 v[12:13], v[38:39], v[206:207], v[12:13]
	v_pk_mul_f32 v[38:39], v[10:11], v[10:11]
	v_add_f32_e32 v1, v3, v1
	v_add_f32_e32 v1, v38, v1
	v_pk_mul_f32 v[36:37], v[12:13], v[12:13]
	v_add_f32_e32 v1, v39, v1
	v_add_f32_e32 v1, v36, v1
	v_pk_mul_f32 v[42:43], v[34:35], v[34:35]
	v_add_f32_e32 v1, v37, v1
	v_add_f32_e32 v1, v42, v1
	v_pk_mul_f32 v[40:41], v[32:33], v[32:33]
	v_add_f32_e32 v1, v43, v1
	v_pk_fma_f32 v[6:7], v[44:45], v[212:213], v[6:7]
	v_add_f32_e32 v1, v40, v1
	v_pk_fma_f32 v[8:9], v[46:47], v[214:215], v[8:9]
	v_pk_mul_f32 v[46:47], v[6:7], v[6:7]
	v_add_f32_e32 v1, v41, v1
	v_add_f32_e32 v1, v46, v1
	v_pk_mul_f32 v[44:45], v[8:9], v[8:9]
	v_add_f32_e32 v1, v47, v1
	v_add_f32_e32 v1, v44, v1
	v_add_f32_e32 v1, v45, v1
	ds_bpermute_b32 v2, v57, v1
	s_waitcnt lgkmcnt(0)
	v_add_f32_e32 v1, v1, v2
	ds_bpermute_b32 v2, v58, v1
	s_waitcnt lgkmcnt(0)
	v_add_f32_e32 v1, v1, v2
	ds_bpermute_b32 v2, v59, v1
	s_waitcnt lgkmcnt(0)
	v_add_f32_e32 v1, v1, v2
	ds_bpermute_b32 v2, v60, v1
	s_waitcnt lgkmcnt(0)
	v_add_f32_e32 v1, v1, v2
	ds_bpermute_b32 v2, v61, v1
	s_waitcnt lgkmcnt(0)
	v_add_f32_e32 v1, v1, v2
	ds_bpermute_b32 v2, v62, v1
	s_waitcnt lgkmcnt(0)
	v_add_f32_e32 v1, v1, v2
	v_fmamk_f32 v1, v1, 0x3a800000, v63
	v_mul_f32_e32 v2, 0x4b800000, v1
	v_cmp_gt_f32_e32 vcc, s7, v1
	s_nop 1
	v_cndmask_b32_e32 v1, v1, v2, vcc
	v_rsq_f32_e32 v1, v1
	s_nop 0
	v_mul_f32_e32 v2, 0x45800000, v1
	v_cndmask_b32_e32 v36, v1, v2, vcc
	v_pk_mul_f32 v[2:3], v[14:15], v[36:37] op_sel_hi:[1,0]
	v_pk_mul_f32 v[4:5], v[16:17], v[36:37] op_sel_hi:[1,0]
	v_pk_mul_f32 v[2:3], v[216:217], v[2:3]
	v_pk_mul_f32 v[4:5], v[218:219], v[4:5]
	v_cvt_pk_bf16_f32 v2, v2, v3
	v_cvt_pk_bf16_f32 v3, v4, v5
	global_store_dwordx2 v[30:31], v[2:3], off offset:2048
	v_pk_mul_f32 v[10:11], v[10:11], v[36:37] op_sel_hi:[1,0]
	v_pk_mul_f32 v[12:13], v[12:13], v[36:37] op_sel_hi:[1,0]
	v_pk_mul_f32 v[6:7], v[6:7], v[36:37] op_sel_hi:[1,0]
	v_pk_mul_f32 v[8:9], v[8:9], v[36:37] op_sel_hi:[1,0]
	v_cmp_lt_i32_e32 vcc, s17, v18
	s_or_b64 s[14:15], vcc, s[14:15]
	v_pk_mul_f32 v[2:3], v[220:221], v[10:11]
	v_pk_mul_f32 v[4:5], v[222:223], v[12:13]
	v_cvt_pk_bf16_f32 v2, v2, v3
	v_cvt_pk_bf16_f32 v3, v4, v5
	global_store_dwordx2 v[30:31], v[2:3], off offset:2560
	v_pk_mul_f32 v[10:11], v[34:35], v[36:37] op_sel_hi:[1,0]
	v_pk_mul_f32 v[12:13], v[32:33], v[36:37] op_sel_hi:[1,0]
	v_pk_mul_f32 v[2:3], v[224:225], v[10:11]
	v_pk_mul_f32 v[4:5], v[226:227], v[12:13]
	v_cvt_pk_bf16_f32 v2, v2, v3
	v_cvt_pk_bf16_f32 v3, v4, v5
	global_store_dwordx2 v[30:31], v[2:3], off offset:3072
	s_nop 1
	v_pk_mul_f32 v[2:3], v[228:229], v[6:7]
	v_pk_mul_f32 v[4:5], v[230:231], v[8:9]
	v_cvt_pk_bf16_f32 v2, v2, v3
	v_cvt_pk_bf16_f32 v3, v4, v5
	global_store_dwordx2 v[30:31], v[2:3], off offset:3584
	s_andn2_b64 exec, exec, s[14:15]
	s_cbranch_execz .LBB0_708
	s_branch .Lp6_topA
